# GDN scan: permute item->WG map (rotate low 4 bits of ticket) so the two WGs that stream the same (b,head) W/QD/KDT/QK operands are bid and bid+8 (same XCD L2)
# speedup vs baseline: 1.0047x; 1.0039x over previous
; DI void gdn_scan(const Params& P, int item, unsigned char* smem, int tt) {
;     const int tid = tt, lane = tid & 63, wave = tid >> 6, r = lane & 31, h2 = lane >> 5;
;     const int bh = item >> 2, vs = item & 3, b = bh >> 2, hd = bh & 3;
;     const int cb = bh * 32;
;     bf16_t* SbT = (bf16_t*)smem;
;     bf16_t* VnT = SbT + 32 * 136;
;     const bool w01 = wave < 2;
;     const int mt = wave & 1;
;     const bf16_t* Ubase = (const bf16_t*)(P.ws + OFF_U);
;     const bf16_t* Abase = (const bf16_t*)(P.ws + (w01 ? OFF_W : OFF_QD));
;     const bf16_t* Kbase = (const bf16_t*)(P.ws + OFF_KDT);
;     const bf16_t* QKbase = (const bf16_t*)(P.ws + OFF_QK);
;     const float* glast = (const float*)(P.ws + OFF_GLAST);
;     bf16_t* og = (bf16_t*)(P.ws + OFF_OG);
;     f32x16 S;
; #pragma unroll
;     for (int e = 0; e < 16; ++e) S[e] = 0.f;
;     for (int i = tid; i < 32 * 136 / 2; i += 256) ((unsigned*)SbT)[i] = 0u;
; __global__ void __launch_bounds__(512, 2) fwd_mega(Params P) {
;     ...
;         if (pr >= 64 + 512) break;
;         if (pr < 64) gdn_scan(P, pr * 2 + team, smem, tt);
.LBB0_558:
	s_andn2_saveexec_b64 s[28:29], s[28:29]
	s_cbranch_execz .LBB0_530
	v_and_b32_e32 v0, 7, v25
	v_bfe_u32 v3, v25, 3, 1
	v_lshl_or_b32 v0, v0, 1, v3
	v_and_or_b32 v25, v25, 48, v0
	v_sub_u32_e32 v0, 0x87f, v130
	v_lshrrev_b32_e32 v0, 8, v0
	v_mul_i32_i24_e32 v6, 0x12c00, v4
	v_add_u32_e32 v3, 2, v0
	v_lshlrev_b32_e32 v7, 2, v130
	v_and_b32_e32 v5, 30, v3
	v_mov_b32_e32 v3, v0
	v_add3_u32 v6, v6, v7, 0
	s_mov_b32 s30, 0
	s_mov_b64 s[2:3], 0
	s_branch .LBB0_561
